# Hyena big item: 3-tap conv loads batched like the small item; per-item prologue waits that only drained the previous item's stores removed
# speedup vs baseline: 1.0185x; 1.0005x over previous
.LBB0_110:
	v_mov_b32_e32 v0, v196
	s_nop 0
	v_readfirstlane_b32 s0, v0
	s_ashr_i32 s24, s0, 8
	s_add_i32 s20, s24, s51
	s_min_i32 s26, s20, 0x7ff
	s_mov_b64 s[0:1], -1
	s_cmpk_gt_i32 s20, 0x3ff
	s_mul_i32 s25, s26, 0x1200
	s_cbranch_scc0 .LBB0_240
	s_add_i32 s28, s26, 0xfffffc00
	v_mov_b32_e32 v14, v196
	s_mul_i32 s0, s28, 0x1200
	v_and_b32_e32 v3, 0xff, v14
	v_readlane_b32 s4, v253, 32
	s_mul_hi_u32 s1, s28, 0x1200
	v_readlane_b32 s5, v253, 33
	s_add_u32 s0, s4, s0
	v_sub_u32_e32 v0, 0x100, v3
	s_addc_u32 s1, s5, s1
	v_cmp_eq_u32_e32 vcc, 0, v3
	v_cmp_ne_u32_e64 s[40:41], 0, v3
	v_mov_b32_e32 v37, 0
	v_lshlrev_b32_e32 v2, 1, v0
	s_and_saveexec_b64 s[20:21], s[40:41]
	s_cbranch_execz .LBB0_113
	global_load_ushort v37, v2, s[0:1]
.LBB0_113:
	s_or_b64 exec, exec, s[20:21]
	v_readlane_b32 s4, v253, 32
	v_readlane_b32 s5, v253, 33
	s_add_u32 s20, s4, s25
	s_addc_u32 s21, s5, 0
	v_lshlrev_b32_e32 v0, 1, v3
	v_lshl_add_u64 v[4:5], s[20:21], 0, v[0:1]
	v_mov_b32_e32 v6, s1
	v_cndmask_b32_e32 v7, v5, v6, vcc
	v_mov_b32_e32 v6, s0
	v_cndmask_b32_e32 v6, v4, v6, vcc
	global_load_ushort v41, v[6:7], off
	s_mov_b32 s29, s31
	v_lshl_add_u32 v6, v3, 4, s50
	v_or_b32_e32 v7, 0xffffff00, v3
	s_mov_b64 s[0:1], 0
	s_waitcnt lgkmcnt(0)
	s_barrier
.LBB0_114:
	v_add_u32_e32 v7, 0x100, v7
	s_movk_i32 s20, 0x5df
	v_cmp_lt_u32_e64 s[42:43], s20, v7
	ds_write_b128 v6, v[210:213]
	s_or_b64 s[0:1], s[42:43], s[0:1]
	v_add_u32_e32 v6, 0x1000, v6
	s_andn2_b64 exec, exec, s[0:1]
	s_cbranch_execnz .LBB0_114
	s_or_b64 exec, exec, s[0:1]
	s_add_i32 s30, s26, 0x400
	s_lshl_b64 s[20:21], s[30:31], 2
	s_add_u32 s0, s89, s20
	s_addc_u32 s1, s90, s21
	s_waitcnt lgkmcnt(0)
	s_barrier
	global_load_dword v15, v1, s[0:1]
	s_lshl_b64 s[0:1], s[28:29], 2
	s_add_u32 s22, s89, s0
	s_addc_u32 s23, s90, s1
	s_add_u32 s20, s91, s20
	v_mov_b32_e32 v6, 0x5000
	v_mov_b32_e32 v7, 0x8000
	s_addc_u32 s21, s92, s21
	global_load_dword v6, v6, s[22:23]
	s_movk_i32 s4, 0xff
	global_load_dword v7, v7, s[22:23]
	v_cmp_ne_u32_e64 s[42:43], s4, v3
	global_load_dword v16, v1, s[20:21]
	v_readlane_b32 s4, v254, 23
	s_lshl_b64 s[20:21], s[30:31], 14
	v_readlane_b32 s6, v254, 25
	v_lshrrev_b32_e32 v8, 5, v3
	v_and_b32_e32 v9, 31, v14
	v_readlane_b32 s7, v254, 26
	s_add_u32 s20, s6, s20
	v_mul_u32_u24_e32 v8, 0x50, v8
	v_lshlrev_b32_e32 v9, 1, v9
	s_addc_u32 s21, s7, s21
	v_add3_u32 v17, v8, v9, s54
	v_lshl_add_u64 v[8:9], s[20:21], 0, v[0:1]
	s_mov_b64 s[20:21], 0
	v_readlane_b32 s5, v254, 24
	s_mov_b64 s[22:23], 0x1000
	v_lshl_add_u64 v[244:245], v[8:9], 0, s[22:23]
	global_load_ushort v128, v[8:9], off offset:-2
	global_load_ushort v129, v[8:9], off
	global_load_ushort v130, v[8:9], off offset:2
	global_load_ushort v131, v[8:9], off offset:510
	global_load_ushort v132, v[8:9], off offset:512
	global_load_ushort v133, v[8:9], off offset:514
	global_load_ushort v134, v[8:9], off offset:1022
	global_load_ushort v135, v[8:9], off offset:1024
	global_load_ushort v136, v[8:9], off offset:1026
	global_load_ushort v137, v[8:9], off offset:1534
	global_load_ushort v138, v[8:9], off offset:1536
	global_load_ushort v139, v[8:9], off offset:1538
	global_load_ushort v140, v[8:9], off offset:2046
	global_load_ushort v141, v[8:9], off offset:2048
	global_load_ushort v142, v[8:9], off offset:2050
	global_load_ushort v143, v[8:9], off offset:2558
	global_load_ushort v144, v[8:9], off offset:2560
	global_load_ushort v145, v[8:9], off offset:2562
	global_load_ushort v146, v[8:9], off offset:3070
	global_load_ushort v147, v[8:9], off offset:3072
	global_load_ushort v148, v[8:9], off offset:3074
	global_load_ushort v149, v[8:9], off offset:3582
	global_load_ushort v150, v[8:9], off offset:3584
	global_load_ushort v151, v[8:9], off offset:3586
	global_load_ushort v152, v[244:245], off offset:-2
	global_load_ushort v153, v[244:245], off
	global_load_ushort v154, v[244:245], off offset:2
	global_load_ushort v155, v[244:245], off offset:510
	global_load_ushort v156, v[244:245], off offset:512
	global_load_ushort v157, v[244:245], off offset:514
	global_load_ushort v158, v[244:245], off offset:1022
	global_load_ushort v159, v[244:245], off offset:1024
	global_load_ushort v160, v[244:245], off offset:1026
	global_load_ushort v161, v[244:245], off offset:1534
	global_load_ushort v162, v[244:245], off offset:1536
	global_load_ushort v163, v[244:245], off offset:1538
	global_load_ushort v164, v[244:245], off offset:2046
	global_load_ushort v165, v[244:245], off offset:2048
	global_load_ushort v166, v[244:245], off offset:2050
	global_load_ushort v167, v[244:245], off offset:2558
	global_load_ushort v168, v[244:245], off offset:2560
	global_load_ushort v169, v[244:245], off offset:2562
	global_load_ushort v170, v[244:245], off offset:3070
	global_load_ushort v171, v[244:245], off offset:3072
	global_load_ushort v172, v[244:245], off offset:3074
	global_load_ushort v173, v[244:245], off offset:3582
	global_load_ushort v174, v[244:245], off offset:3584
	global_load_ushort v175, v[244:245], off offset:3586
	s_waitcnt vmcnt(0)
	v_lshlrev_b32_e32 v0, 16, v128
	v_lshlrev_b32_e32 v12, 16, v129
	v_lshlrev_b32_e32 v13, 16, v130
	v_cndmask_b32_e64 v0, 0, v0, s[40:41]
	v_cndmask_b32_e64 v13, 0, v13, s[42:43]
	v_pk_mul_f32 v[12:13], v[6:7], v[12:13]
	s_nop 0
	v_fma_f32 v0, v15, v0, v12
	v_add_f32_e32 v0, v0, v13
	v_add_f32_e32 v0, v16, v0
	v_cvt_pk_bf16_f32 v0, v0, s0
	ds_write_b16 v17, v0
	v_lshlrev_b32_e32 v0, 16, v131
	v_lshlrev_b32_e32 v12, 16, v132
	v_lshlrev_b32_e32 v13, 16, v133
	v_cndmask_b32_e64 v0, 0, v0, s[40:41]
	v_cndmask_b32_e64 v13, 0, v13, s[42:43]
	v_pk_mul_f32 v[12:13], v[6:7], v[12:13]
	s_nop 0
	v_fma_f32 v0, v15, v0, v12
	v_add_f32_e32 v0, v0, v13
	v_add_f32_e32 v0, v16, v0
	v_cvt_pk_bf16_f32 v0, v0, s0
	ds_write_b16 v17, v0 offset:1760
	v_lshlrev_b32_e32 v0, 16, v134
	v_lshlrev_b32_e32 v12, 16, v135
	v_lshlrev_b32_e32 v13, 16, v136
	v_cndmask_b32_e64 v0, 0, v0, s[40:41]
	v_cndmask_b32_e64 v13, 0, v13, s[42:43]
	v_pk_mul_f32 v[12:13], v[6:7], v[12:13]
	s_nop 0
	v_fma_f32 v0, v15, v0, v12
	v_add_f32_e32 v0, v0, v13
	v_add_f32_e32 v0, v16, v0
	v_cvt_pk_bf16_f32 v0, v0, s0
	ds_write_b16 v17, v0 offset:3520
	v_lshlrev_b32_e32 v0, 16, v137
	v_lshlrev_b32_e32 v12, 16, v138
	v_lshlrev_b32_e32 v13, 16, v139
	v_cndmask_b32_e64 v0, 0, v0, s[40:41]
	v_cndmask_b32_e64 v13, 0, v13, s[42:43]
	v_pk_mul_f32 v[12:13], v[6:7], v[12:13]
	s_nop 0
	v_fma_f32 v0, v15, v0, v12
	v_add_f32_e32 v0, v0, v13
	v_add_f32_e32 v0, v16, v0
	v_cvt_pk_bf16_f32 v0, v0, s0
	ds_write_b16 v17, v0 offset:5280
	v_add_u32_e32 v17, 0x1b80, v17
	v_lshlrev_b32_e32 v0, 16, v140
	v_lshlrev_b32_e32 v12, 16, v141
	v_lshlrev_b32_e32 v13, 16, v142
	v_cndmask_b32_e64 v0, 0, v0, s[40:41]
	v_cndmask_b32_e64 v13, 0, v13, s[42:43]
	v_pk_mul_f32 v[12:13], v[6:7], v[12:13]
	s_nop 0
	v_fma_f32 v0, v15, v0, v12
	v_add_f32_e32 v0, v0, v13
	v_add_f32_e32 v0, v16, v0
	v_cvt_pk_bf16_f32 v0, v0, s0
	ds_write_b16 v17, v0
	v_lshlrev_b32_e32 v0, 16, v143
	v_lshlrev_b32_e32 v12, 16, v144
	v_lshlrev_b32_e32 v13, 16, v145
	v_cndmask_b32_e64 v0, 0, v0, s[40:41]
	v_cndmask_b32_e64 v13, 0, v13, s[42:43]
	v_pk_mul_f32 v[12:13], v[6:7], v[12:13]
	s_nop 0
	v_fma_f32 v0, v15, v0, v12
	v_add_f32_e32 v0, v0, v13
	v_add_f32_e32 v0, v16, v0
	v_cvt_pk_bf16_f32 v0, v0, s0
	ds_write_b16 v17, v0 offset:1760
	v_lshlrev_b32_e32 v0, 16, v146
	v_lshlrev_b32_e32 v12, 16, v147
	v_lshlrev_b32_e32 v13, 16, v148
	v_cndmask_b32_e64 v0, 0, v0, s[40:41]
	v_cndmask_b32_e64 v13, 0, v13, s[42:43]
	v_pk_mul_f32 v[12:13], v[6:7], v[12:13]
	s_nop 0
	v_fma_f32 v0, v15, v0, v12
	v_add_f32_e32 v0, v0, v13
	v_add_f32_e32 v0, v16, v0
	v_cvt_pk_bf16_f32 v0, v0, s0
	ds_write_b16 v17, v0 offset:3520
	v_lshlrev_b32_e32 v0, 16, v149
	v_lshlrev_b32_e32 v12, 16, v150
	v_lshlrev_b32_e32 v13, 16, v151
	v_cndmask_b32_e64 v0, 0, v0, s[40:41]
	v_cndmask_b32_e64 v13, 0, v13, s[42:43]
	v_pk_mul_f32 v[12:13], v[6:7], v[12:13]
	s_nop 0
	v_fma_f32 v0, v15, v0, v12
	v_add_f32_e32 v0, v0, v13
	v_add_f32_e32 v0, v16, v0
	v_cvt_pk_bf16_f32 v0, v0, s0
	ds_write_b16 v17, v0 offset:5280
	v_add_u32_e32 v17, 0x1b80, v17
	v_lshlrev_b32_e32 v0, 16, v152
	v_lshlrev_b32_e32 v12, 16, v153
	v_lshlrev_b32_e32 v13, 16, v154
	v_cndmask_b32_e64 v0, 0, v0, s[40:41]
	v_cndmask_b32_e64 v13, 0, v13, s[42:43]
	v_pk_mul_f32 v[12:13], v[6:7], v[12:13]
	s_nop 0
	v_fma_f32 v0, v15, v0, v12
	v_add_f32_e32 v0, v0, v13
	v_add_f32_e32 v0, v16, v0
	v_cvt_pk_bf16_f32 v0, v0, s0
	ds_write_b16 v17, v0
	v_lshlrev_b32_e32 v0, 16, v155
	v_lshlrev_b32_e32 v12, 16, v156
	v_lshlrev_b32_e32 v13, 16, v157
	v_cndmask_b32_e64 v0, 0, v0, s[40:41]
	v_cndmask_b32_e64 v13, 0, v13, s[42:43]
	v_pk_mul_f32 v[12:13], v[6:7], v[12:13]
	s_nop 0
	v_fma_f32 v0, v15, v0, v12
	v_add_f32_e32 v0, v0, v13
	v_add_f32_e32 v0, v16, v0
	v_cvt_pk_bf16_f32 v0, v0, s0
	ds_write_b16 v17, v0 offset:1760
	v_lshlrev_b32_e32 v0, 16, v158
	v_lshlrev_b32_e32 v12, 16, v159
	v_lshlrev_b32_e32 v13, 16, v160
	v_cndmask_b32_e64 v0, 0, v0, s[40:41]
	v_cndmask_b32_e64 v13, 0, v13, s[42:43]
	v_pk_mul_f32 v[12:13], v[6:7], v[12:13]
	s_nop 0
	v_fma_f32 v0, v15, v0, v12
	v_add_f32_e32 v0, v0, v13
	v_add_f32_e32 v0, v16, v0
	v_cvt_pk_bf16_f32 v0, v0, s0
	ds_write_b16 v17, v0 offset:3520
	v_lshlrev_b32_e32 v0, 16, v161
	v_lshlrev_b32_e32 v12, 16, v162
	v_lshlrev_b32_e32 v13, 16, v163
	v_cndmask_b32_e64 v0, 0, v0, s[40:41]
	v_cndmask_b32_e64 v13, 0, v13, s[42:43]
	v_pk_mul_f32 v[12:13], v[6:7], v[12:13]
	s_nop 0
	v_fma_f32 v0, v15, v0, v12
	v_add_f32_e32 v0, v0, v13
	v_add_f32_e32 v0, v16, v0
	v_cvt_pk_bf16_f32 v0, v0, s0
	ds_write_b16 v17, v0 offset:5280
	v_add_u32_e32 v17, 0x1b80, v17
	v_lshlrev_b32_e32 v0, 16, v164
	v_lshlrev_b32_e32 v12, 16, v165
	v_lshlrev_b32_e32 v13, 16, v166
	v_cndmask_b32_e64 v0, 0, v0, s[40:41]
	v_cndmask_b32_e64 v13, 0, v13, s[42:43]
	v_pk_mul_f32 v[12:13], v[6:7], v[12:13]
	s_nop 0
	v_fma_f32 v0, v15, v0, v12
	v_add_f32_e32 v0, v0, v13
	v_add_f32_e32 v0, v16, v0
	v_cvt_pk_bf16_f32 v0, v0, s0
	ds_write_b16 v17, v0
	v_lshlrev_b32_e32 v0, 16, v167
	v_lshlrev_b32_e32 v12, 16, v168
	v_lshlrev_b32_e32 v13, 16, v169
	v_cndmask_b32_e64 v0, 0, v0, s[40:41]
	v_cndmask_b32_e64 v13, 0, v13, s[42:43]
	v_pk_mul_f32 v[12:13], v[6:7], v[12:13]
	s_nop 0
	v_fma_f32 v0, v15, v0, v12
	v_add_f32_e32 v0, v0, v13
	v_add_f32_e32 v0, v16, v0
	v_cvt_pk_bf16_f32 v0, v0, s0
	ds_write_b16 v17, v0 offset:1760
	v_lshlrev_b32_e32 v0, 16, v170
	v_lshlrev_b32_e32 v12, 16, v171
	v_lshlrev_b32_e32 v13, 16, v172
	v_cndmask_b32_e64 v0, 0, v0, s[40:41]
	v_cndmask_b32_e64 v13, 0, v13, s[42:43]
	v_pk_mul_f32 v[12:13], v[6:7], v[12:13]
	s_nop 0
	v_fma_f32 v0, v15, v0, v12
	v_add_f32_e32 v0, v0, v13
	v_add_f32_e32 v0, v16, v0
	v_cvt_pk_bf16_f32 v0, v0, s0
	ds_write_b16 v17, v0 offset:3520
	v_lshlrev_b32_e32 v0, 16, v173
	v_lshlrev_b32_e32 v12, 16, v174
	v_lshlrev_b32_e32 v13, 16, v175
	v_cndmask_b32_e64 v0, 0, v0, s[40:41]
	v_cndmask_b32_e64 v13, 0, v13, s[42:43]
	v_pk_mul_f32 v[12:13], v[6:7], v[12:13]
	s_nop 0
	v_fma_f32 v0, v15, v0, v12
	v_add_f32_e32 v0, v0, v13
	v_add_f32_e32 v0, v16, v0
	v_cvt_pk_bf16_f32 v0, v0, s0
	ds_write_b16 v17, v0 offset:5280
	v_add_u32_e32 v17, 0x1b80, v17

.LBB0_240:
	s_and_b64 vcc, exec, s[0:1]
	s_cbranch_vccz .LBB0_109
	v_mov_b32_e32 v5, v196
	s_ashr_i32 s27, s26, 31
	v_and_b32_e32 v3, 0xff, v5
	v_readlane_b32 s4, v253, 32
	s_mul_hi_i32 s1, s26, 0x1200
	v_readlane_b32 s5, v253, 33
	s_add_u32 s0, s4, s25
	v_sub_u32_e32 v0, 0x800, v3
	s_addc_u32 s1, s5, s1
	v_cmp_eq_u32_e64 s[46:47], 0, v3
	v_cmp_ne_u32_e64 s[40:41], 0, v3
	v_mov_b32_e32 v116, 0
	v_lshlrev_b32_e32 v2, 1, v0
	s_and_saveexec_b64 s[20:21], s[40:41]
	s_cbranch_execz .LBB0_243
	global_load_ushort v116, v2, s[0:1] offset:512
.LBB0_243:
	s_or_b64 exec, exec, s[20:21]
	s_add_u32 s22, s0, 0x200
	s_addc_u32 s23, s1, 0
	s_add_i32 s20, s26, 0x400
	s_mul_hi_i32 s21, s20, 0x1200
	s_mulk_i32 s20, 0x1200
	v_readlane_b32 s4, v253, 32
	v_readlane_b32 s5, v253, 33
	s_add_u32 s20, s4, s20
	v_or_b32_e32 v4, 0x800, v3
	s_addc_u32 s21, s5, s21
	v_lshlrev_b32_e32 v0, 1, v4
	s_movk_i32 s4, 0xf200
	v_lshl_add_u64 v[20:21], s[20:21], 0, v[0:1]
	s_mov_b32 s5, -1
	v_lshl_add_u64 v[20:21], v[20:21], 0, s[4:5]
	v_mov_b32_e32 v0, s23
	v_cndmask_b32_e64 v21, v21, v0, s[46:47]
	v_mov_b32_e32 v0, s22
	v_sub_u32_e32 v18, 0x700, v3
	v_cndmask_b32_e64 v20, v20, v0, s[46:47]
	v_lshlrev_b32_e32 v7, 1, v18
	v_sub_u32_e32 v16, 0x600, v3
	v_sub_u32_e32 v14, 0x500, v3
	v_sub_u32_e32 v12, 0x400, v3
	v_sub_u32_e32 v10, 0x300, v3
	v_sub_u32_e32 v8, 0x200, v3
	v_sub_u32_e32 v6, 0x100, v3
	global_load_ushort v117, v[20:21], off
	v_or_b32_e32 v20, 0x900, v3
	v_lshlrev_b32_e32 v9, 1, v16
	v_lshlrev_b32_e32 v11, 1, v14
	v_lshlrev_b32_e32 v13, 1, v12
	v_lshlrev_b32_e32 v15, 1, v10
	v_lshlrev_b32_e32 v17, 1, v8
	v_lshlrev_b32_e32 v19, 1, v6
	v_lshlrev_b32_e32 v0, 1, v20
	global_load_ushort v118, v7, s[0:1] offset:512
	global_load_ushort v119, v9, s[0:1] offset:512
	global_load_ushort v120, v11, s[0:1] offset:512
	global_load_ushort v121, v13, s[0:1] offset:512
	global_load_ushort v122, v15, s[0:1] offset:512
	global_load_ushort v123, v17, s[0:1] offset:512
	global_load_ushort v124, v19, s[0:1] offset:512
	global_load_ushort v125, v0, s[20:21] offset:-3584
	s_waitcnt lgkmcnt(0)
	v_or_b32_e32 v32, 0xa00, v3
	v_lshlrev_b32_e32 v0, 1, v32
	v_or_b32_e32 v30, 0xb00, v3
	v_or_b32_e32 v28, 0xc00, v3
	v_or_b32_e32 v26, 0xd00, v3
	v_or_b32_e32 v24, 0xe00, v3
	v_or_b32_e32 v22, 0xf00, v3
	v_lshlrev_b32_e32 v7, 1, v30
	v_lshlrev_b32_e32 v9, 1, v28
	v_lshlrev_b32_e32 v11, 1, v26
	v_lshlrev_b32_e32 v13, 1, v24
	v_lshlrev_b32_e32 v15, 1, v22
	global_load_ushort v126, v0, s[20:21] offset:-3584
	global_load_ushort v127, v7, s[20:21] offset:-3584
	global_load_ushort v128, v9, s[20:21] offset:-3584
	global_load_ushort v129, v11, s[20:21] offset:-3584
	global_load_ushort v130, v13, s[20:21] offset:-3584
	global_load_ushort v131, v15, s[20:21] offset:-3584
	v_lshl_add_u32 v0, v3, 4, s95
	v_or_b32_e32 v7, 0xffffff00, v3
	s_mov_b64 s[0:1], 0
	s_barrier
.LBB0_244:
	v_add_u32_e32 v7, 0x100, v7
	s_movk_i32 s20, 0x66b
	v_cmp_lt_u32_e32 vcc, s20, v7
	ds_write_b128 v0, v[210:213]
	s_or_b64 s[0:1], vcc, s[0:1]
	v_add_u32_e32 v0, 0x1000, v0
	s_andn2_b64 exec, exec, s[0:1]
	s_cbranch_execnz .LBB0_244
	s_or_b64 exec, exec, s[0:1]
	s_add_i32 s20, s26, 0x800
	s_ashr_i32 s21, s20, 31
	s_lshl_b64 s[22:23], s[20:21], 2
	s_add_u32 s42, s89, s22
	s_addc_u32 s43, s90, s23
	s_lshl_b64 s[0:1], s[26:27], 2
	s_add_u32 s28, s89, s0
	s_addc_u32 s29, s90, s1
	s_add_u32 s22, s91, s22
	v_mov_b32_e32 v0, 0x5000
	s_waitcnt lgkmcnt(0)
	s_barrier
	s_addc_u32 s23, s92, s23
	global_load_dword v34, v1, s[42:43]
	global_load_dword v9, v0, s[28:29]
	global_load_dword v11, v1, s[22:23]
	v_mov_b32_e32 v0, 0x8000
	global_load_dword v35, v0, s[28:29]
	s_ashr_i32 s21, s51, 31
	s_ashr_i32 s23, s24, 31
	s_add_u32 s22, s51, s24
	s_addc_u32 s23, s21, s23
	v_mov_b64_e32 v[36:37], 0x7ff
	v_cmp_lt_i64_e32 vcc, s[22:23], v[36:37]
	s_and_b64 s[24:25], vcc, exec
	s_cselect_b32 s23, s23, 0
	s_cselect_b32 s22, s22, 0x7ff
	v_readlane_b32 s4, v254, 23
	s_lshl_b64 s[22:23], s[22:23], 14
	v_readlane_b32 s6, v254, 25
	v_readlane_b32 s7, v254, 26
	s_add_u32 s22, s6, s22
	v_lshlrev_b32_e32 v0, 1, v3
	s_addc_u32 s23, s7, s23
	v_and_b32_e32 v7, 31, v5
	v_lshl_add_u64 v[36:37], s[22:23], 0, v[0:1]
	v_or_b32_e32 v0, 0x200, v3
	v_or_b32_e32 v15, 0x100, v3
	v_lshl_add_u32 v13, v7, 1, s33
	s_mov_b32 s21, 0
	v_lshrrev_b32_e32 v0, 5, v0
	v_lshrrev_b32_e32 v15, 5, v15
	s_mov_b64 s[22:23], 0
	v_mov_b32_e32 v17, v3
	v_readlane_b32 s5, v254, 24
	v_add_co_u32_e32 v244, vcc, 0x2002000, v36
	s_nop 1
	v_addc_co_u32_e32 v245, vcc, 0, v37, vcc
	v_add_co_u32_e32 v246, vcc, 0x1000, v244
	s_nop 1
	v_addc_co_u32_e32 v247, vcc, 0, v245, vcc
	global_load_ushort v132, v[244:245], off offset:-2
	global_load_ushort v133, v[244:245], off
	global_load_ushort v134, v[244:245], off offset:2
	global_load_ushort v135, v[244:245], off offset:510
	global_load_ushort v136, v[244:245], off offset:512
	global_load_ushort v137, v[244:245], off offset:514
	global_load_ushort v138, v[244:245], off offset:1022
	global_load_ushort v139, v[244:245], off offset:1024
	global_load_ushort v140, v[244:245], off offset:1026
	global_load_ushort v141, v[244:245], off offset:1534
	global_load_ushort v142, v[244:245], off offset:1536
	global_load_ushort v143, v[244:245], off offset:1538
	global_load_ushort v144, v[244:245], off offset:2046
	global_load_ushort v145, v[244:245], off offset:2048
	global_load_ushort v146, v[244:245], off offset:2050
	global_load_ushort v147, v[244:245], off offset:2558
	global_load_ushort v148, v[244:245], off offset:2560
	global_load_ushort v149, v[244:245], off offset:2562
	global_load_ushort v150, v[244:245], off offset:3070
	global_load_ushort v151, v[244:245], off offset:3072
	global_load_ushort v152, v[244:245], off offset:3074
	global_load_ushort v153, v[244:245], off offset:3582
	global_load_ushort v154, v[244:245], off offset:3584
	global_load_ushort v155, v[244:245], off offset:3586
	global_load_ushort v156, v[246:247], off offset:-2
	global_load_ushort v157, v[246:247], off
	global_load_ushort v158, v[246:247], off offset:2
	global_load_ushort v159, v[246:247], off offset:510
	global_load_ushort v160, v[246:247], off offset:512
	global_load_ushort v161, v[246:247], off offset:514
	global_load_ushort v162, v[246:247], off offset:1022
	global_load_ushort v163, v[246:247], off offset:1024
	global_load_ushort v180, v[246:247], off offset:1026
	global_load_ushort v181, v[246:247], off offset:1534
	global_load_ushort v182, v[246:247], off offset:1536
	global_load_ushort v183, v[246:247], off offset:1538
	global_load_ushort v184, v[246:247], off offset:2046
	global_load_ushort v185, v[246:247], off offset:2048
	global_load_ushort v186, v[246:247], off offset:2050
	global_load_ushort v187, v[246:247], off offset:2558
	global_load_ushort v188, v[246:247], off offset:2560
	global_load_ushort v189, v[246:247], off offset:2562
	global_load_ushort v190, v[246:247], off offset:3070
	global_load_ushort v191, v[246:247], off offset:3072
	global_load_ushort v192, v[246:247], off offset:3074
	global_load_ushort v193, v[246:247], off offset:3582
	global_load_ushort v194, v[246:247], off offset:3584
	global_load_ushort v195, v[246:247], off offset:3586
	v_and_b32_e32 v19, 31, v3
	v_lshrrev_b32_e32 v21, 5, v3
	v_lshl_add_u32 v19, v19, 1, s33
	s_movk_i32 s4, 0x50
	v_mad_u32_u24 v23, v21, s4, v19
	v_cmp_ne_u32_e64 s[24:25], 0, v3
	v_cmp_ne_u32_e32 vcc, 0xff, v3
	s_waitcnt vmcnt(0)
	v_lshlrev_b32_e32 v42, 16, v132
	v_lshlrev_b32_e32 v43, 16, v134
	v_lshlrev_b32_e32 v21, 16, v133
	v_cndmask_b32_e64 v42, 0, v42, s[24:25]
	v_pk_mul_f32 v[42:43], v[34:35], v[42:43]
	s_nop 0
	v_fma_f32 v21, v9, v21, v42
	v_add_f32_e32 v21, v21, v43
	v_add_f32_e32 v21, v11, v21
	v_cvt_pk_bf16_f32 v21, v21, s0
	ds_write_b16 v23, v21 offset:38064
	v_lshlrev_b32_e32 v42, 16, v135
	v_lshlrev_b32_e32 v43, 16, v137
	v_lshlrev_b32_e32 v21, 16, v136
	v_pk_mul_f32 v[42:43], v[34:35], v[42:43]
	s_nop 0
	v_fma_f32 v21, v9, v21, v42
	v_add_f32_e32 v21, v21, v43
	v_add_f32_e32 v21, v11, v21
	v_cvt_pk_bf16_f32 v21, v21, s0
	ds_write_b16 v23, v21 offset:38704
	v_lshlrev_b32_e32 v42, 16, v138
	v_lshlrev_b32_e32 v43, 16, v140
	v_lshlrev_b32_e32 v21, 16, v139
	v_pk_mul_f32 v[42:43], v[34:35], v[42:43]
	s_nop 0
	v_fma_f32 v21, v9, v21, v42
	v_add_f32_e32 v21, v21, v43
	v_add_f32_e32 v21, v11, v21
	v_cvt_pk_bf16_f32 v21, v21, s0
	ds_write_b16 v23, v21 offset:39344
	v_lshlrev_b32_e32 v42, 16, v141
	v_lshlrev_b32_e32 v43, 16, v143
	v_lshlrev_b32_e32 v21, 16, v142
	v_pk_mul_f32 v[42:43], v[34:35], v[42:43]
	s_nop 0
	v_fma_f32 v21, v9, v21, v42
	v_add_f32_e32 v21, v21, v43
	v_add_f32_e32 v21, v11, v21
	v_cvt_pk_bf16_f32 v21, v21, s0
	ds_write_b16 v23, v21 offset:39984
	v_lshlrev_b32_e32 v42, 16, v144
	v_lshlrev_b32_e32 v43, 16, v146
	v_lshlrev_b32_e32 v21, 16, v145
	v_pk_mul_f32 v[42:43], v[34:35], v[42:43]
	s_nop 0
	v_fma_f32 v21, v9, v21, v42
	v_add_f32_e32 v21, v21, v43
	v_add_f32_e32 v21, v11, v21
	v_cvt_pk_bf16_f32 v21, v21, s0
	ds_write_b16 v23, v21 offset:40624
	v_lshlrev_b32_e32 v42, 16, v147
	v_lshlrev_b32_e32 v43, 16, v149
	v_lshlrev_b32_e32 v21, 16, v148
	v_pk_mul_f32 v[42:43], v[34:35], v[42:43]
	s_nop 0
	v_fma_f32 v21, v9, v21, v42
	v_add_f32_e32 v21, v21, v43
	v_add_f32_e32 v21, v11, v21
	v_cvt_pk_bf16_f32 v21, v21, s0
	ds_write_b16 v23, v21 offset:41264
	v_lshlrev_b32_e32 v42, 16, v150
	v_lshlrev_b32_e32 v43, 16, v152
	v_lshlrev_b32_e32 v21, 16, v151
	v_pk_mul_f32 v[42:43], v[34:35], v[42:43]
	s_nop 0
	v_fma_f32 v21, v9, v21, v42
	v_add_f32_e32 v21, v21, v43
	v_add_f32_e32 v21, v11, v21
	v_cvt_pk_bf16_f32 v21, v21, s0
	ds_write_b16 v23, v21 offset:41904
	v_lshlrev_b32_e32 v42, 16, v153
	v_lshlrev_b32_e32 v43, 16, v155
	v_lshlrev_b32_e32 v21, 16, v154
	v_cndmask_b32_e32 v43, 0, v43, vcc
	v_pk_mul_f32 v[42:43], v[34:35], v[42:43]
	s_nop 0
	v_fma_f32 v21, v9, v21, v42
	v_add_f32_e32 v21, v21, v43
	v_add_f32_e32 v21, v11, v21
	v_cvt_pk_bf16_f32 v21, v21, s0
	ds_write_b16 v23, v21 offset:42544
	v_lshlrev_b32_e32 v42, 16, v156
	v_lshlrev_b32_e32 v43, 16, v158
	v_lshlrev_b32_e32 v21, 16, v157
	v_cndmask_b32_e64 v42, 0, v42, s[24:25]
	v_pk_mul_f32 v[42:43], v[34:35], v[42:43]
	s_nop 0
	v_fma_f32 v21, v9, v21, v42
	v_add_f32_e32 v21, v21, v43
	v_add_f32_e32 v21, v11, v21
	v_cvt_pk_bf16_f32 v21, v21, s0
	ds_write_b16 v23, v21 offset:53264
	v_lshlrev_b32_e32 v42, 16, v159
	v_lshlrev_b32_e32 v43, 16, v161
	v_lshlrev_b32_e32 v21, 16, v160
	v_pk_mul_f32 v[42:43], v[34:35], v[42:43]
	s_nop 0
	v_fma_f32 v21, v9, v21, v42
	v_add_f32_e32 v21, v21, v43
	v_add_f32_e32 v21, v11, v21
	v_cvt_pk_bf16_f32 v21, v21, s0
	ds_write_b16 v23, v21 offset:53904
	v_lshlrev_b32_e32 v42, 16, v162
	v_lshlrev_b32_e32 v43, 16, v180
	v_lshlrev_b32_e32 v21, 16, v163
	v_pk_mul_f32 v[42:43], v[34:35], v[42:43]
	s_nop 0
	v_fma_f32 v21, v9, v21, v42
	v_add_f32_e32 v21, v21, v43
	v_add_f32_e32 v21, v11, v21
	v_cvt_pk_bf16_f32 v21, v21, s0
	ds_write_b16 v23, v21 offset:54544
	v_lshlrev_b32_e32 v42, 16, v181
	v_lshlrev_b32_e32 v43, 16, v183
	v_lshlrev_b32_e32 v21, 16, v182
	v_pk_mul_f32 v[42:43], v[34:35], v[42:43]
	s_nop 0
	v_fma_f32 v21, v9, v21, v42
	v_add_f32_e32 v21, v21, v43
	v_add_f32_e32 v21, v11, v21
	v_cvt_pk_bf16_f32 v21, v21, s0
	ds_write_b16 v23, v21 offset:55184
	v_lshlrev_b32_e32 v42, 16, v184
	v_lshlrev_b32_e32 v43, 16, v186
	v_lshlrev_b32_e32 v21, 16, v185
	v_pk_mul_f32 v[42:43], v[34:35], v[42:43]
	s_nop 0
	v_fma_f32 v21, v9, v21, v42
	v_add_f32_e32 v21, v21, v43
	v_add_f32_e32 v21, v11, v21
	v_cvt_pk_bf16_f32 v21, v21, s0
	ds_write_b16 v23, v21 offset:55824
	v_lshlrev_b32_e32 v42, 16, v187
	v_lshlrev_b32_e32 v43, 16, v189
	v_lshlrev_b32_e32 v21, 16, v188
	v_pk_mul_f32 v[42:43], v[34:35], v[42:43]
	s_nop 0
	v_fma_f32 v21, v9, v21, v42
	v_add_f32_e32 v21, v21, v43
	v_add_f32_e32 v21, v11, v21
	v_cvt_pk_bf16_f32 v21, v21, s0
	ds_write_b16 v23, v21 offset:56464
	v_lshlrev_b32_e32 v42, 16, v190
	v_lshlrev_b32_e32 v43, 16, v192
	v_lshlrev_b32_e32 v21, 16, v191
	v_pk_mul_f32 v[42:43], v[34:35], v[42:43]
	s_nop 0
	v_fma_f32 v21, v9, v21, v42
	v_add_f32_e32 v21, v21, v43
	v_add_f32_e32 v21, v11, v21
	v_cvt_pk_bf16_f32 v21, v21, s0
	ds_write_b16 v23, v21 offset:57104
	v_lshlrev_b32_e32 v42, 16, v193
	v_lshlrev_b32_e32 v43, 16, v195
	v_lshlrev_b32_e32 v21, 16, v194
	v_cndmask_b32_e32 v43, 0, v43, vcc
	v_pk_mul_f32 v[42:43], v[34:35], v[42:43]
	s_nop 0
	v_fma_f32 v21, v9, v21, v42
	v_add_f32_e32 v21, v21, v43
	v_add_f32_e32 v21, v11, v21
	v_cvt_pk_bf16_f32 v21, v21, s0
	ds_write_b16 v23, v21 offset:57744
